# layer-0 x->bf16 row loop: the 8 row loads issued together with counted waits (one quad renamed), same summation order
# speedup vs baseline: 1.0107x; 1.0107x over previous
; DI unsigned cvt_pk_bf16(float lo, float hi) { unsigned r; asm volatile("v_cvt_pk_bf16_f32 %0, %1, %2" : "=v"(r) : "v"(lo), "v"(hi)); return r; }
; DI void conv_phase(PP P, int l, unsigned char* lds, int G, int cid) {
;     ...
;         for (int m = gw; m < MTOK; m += NGW) {
;             const f32x4* xr = (const f32x4*)(x + (size_t)m * DM) + lane;
;             f32x4 v[8]; float s = 0.f;
; #pragma unroll
;             for (int j = 0; j < 8; ++j) { v[j] = xr[64 * j]; s += (v[j].x * v[j].x + v[j].y * v[j].y) + (v[j].z * v[j].z + v[j].w * v[j].w); }
;             s = wave_sum(s);
;             if (lane == 0) rowss[m] = (u64)(s * RS_SCALE + 0.5f);
;             u32x2* o = (u32x2*)(XB + (size_t)m * DM) + lane;
; #pragma unroll
;             for (int j = 0; j < 8; ++j) { u32x2 w; w.x = cvt_pk_bf16(v[j].x, v[j].y); w.y = cvt_pk_bf16(v[j].z, v[j].w); o[64 * j] = w; }
;         }
.LBB0_518:
	s_or_b64 exec, exec, s[28:29]
	s_waitcnt lgkmcnt(0)
	v_lshl_add_u64 v[46:47], s[70:71], 0, v[36:37]
	v_cvt_pk_bf16_f32 v14, v14, v15
	v_cvt_pk_bf16_f32 v15, v16, v17
	v_add_co_u32_e32 v16, vcc, 0x7400000, v46
	v_add_u32_e32 v68, s42, v68
	s_nop 0
	v_addc_co_u32_e32 v17, vcc, 0, v47, vcc
	global_store_dwordx2 v[16:17], v[14:15], off
	v_cvt_pk_bf16_f32 v10, v10, v11
	v_cvt_pk_bf16_f32 v11, v12, v13
	global_store_dwordx2 v[16:17], v[10:11], off offset:512
	v_cvt_pk_bf16_f32 v6, v6, v7
	v_cvt_pk_bf16_f32 v7, v8, v9
	global_store_dwordx2 v[16:17], v[6:7], off offset:1024
	v_cvt_pk_bf16_f32 v2, v48, v49
	v_cvt_pk_bf16_f32 v3, v50, v51
	global_store_dwordx2 v[16:17], v[2:3], off offset:1536
	v_cvt_pk_bf16_f32 v2, v18, v19
	v_cvt_pk_bf16_f32 v3, v20, v21
	s_movk_i32 s4, 0x3fff
	global_store_dwordx2 v[16:17], v[2:3], off offset:2048
	v_cvt_pk_bf16_f32 v2, v22, v23
	v_cvt_pk_bf16_f32 v3, v24, v25
	v_cmp_lt_i32_e32 vcc, s4, v68
	global_store_dwordx2 v[16:17], v[2:3], off offset:2560
	v_cvt_pk_bf16_f32 v2, v26, v27
	v_cvt_pk_bf16_f32 v3, v28, v29
	v_lshl_add_u64 v[34:35], v[34:35], 0, s[0:1]
	v_lshl_add_u64 v[36:37], v[36:37], 0, s[14:15]
	s_or_b64 s[18:19], vcc, s[18:19]
	v_lshl_add_u64 v[38:39], v[38:39], 0, s[16:17]
	global_store_dwordx2 v[16:17], v[2:3], off offset:3072
	v_cvt_pk_bf16_f32 v2, v30, v31
	v_cvt_pk_bf16_f32 v3, v32, v33
	global_store_dwordx2 v[16:17], v[2:3], off offset:3584
	s_andn2_b64 exec, exec, s[18:19]
	s_cbranch_execz .LBB0_521
.LBB0_519:
	v_add_co_u32_e32 v2, vcc, 0xfffff000, v38
	s_nop 1
	v_addc_co_u32_e32 v3, vcc, -1, v39, vcc
	global_load_dwordx4 v[14:17], v[2:3], off offset:-3072
	global_load_dwordx4 v[10:13], v[2:3], off offset:-2048
	global_load_dwordx4 v[6:9], v[2:3], off offset:-1024
	global_load_dwordx4 v[48:51], v[38:39], off offset:-4096
	global_load_dwordx4 v[18:21], v[38:39], off offset:-3072
	global_load_dwordx4 v[22:25], v[38:39], off offset:-2048
	global_load_dwordx4 v[26:29], v[38:39], off offset:-1024
	global_load_dwordx4 v[30:33], v[38:39], off
	s_waitcnt vmcnt(7)
	v_mul_f32_e32 v54, v15, v15
	v_mul_f32_e32 v53, v17, v17
	v_fmac_f32_e32 v54, v14, v14
	v_fmac_f32_e32 v53, v16, v16
	v_add_f32_e32 v54, v54, v53
	s_waitcnt vmcnt(6)
	v_mul_f32_e32 v52, v11, v11
	v_mul_f32_e32 v53, v13, v13
	v_fmac_f32_e32 v52, v10, v10
	v_fmac_f32_e32 v53, v12, v12
	v_add_f32_e32 v52, v52, v53
	v_add_f32_e32 v54, v54, v52
	s_waitcnt vmcnt(5)
	v_mul_f32_e32 v52, v7, v7
	v_mul_f32_e32 v53, v9, v9
	v_fmac_f32_e32 v52, v6, v6
	v_fmac_f32_e32 v53, v8, v8
	v_add_f32_e32 v52, v52, v53
	v_add_f32_e32 v54, v54, v52
	s_waitcnt vmcnt(4)
	v_mul_f32_e32 v52, v49, v49
	v_mul_f32_e32 v53, v51, v51
	v_fmac_f32_e32 v52, v48, v48
	v_fmac_f32_e32 v53, v50, v50
	v_add_f32_e32 v52, v52, v53
	v_add_f32_e32 v54, v54, v52
	s_waitcnt vmcnt(3)
	v_mul_f32_e32 v52, v19, v19
	v_mul_f32_e32 v53, v21, v21
	v_fmac_f32_e32 v52, v18, v18
	v_fmac_f32_e32 v53, v20, v20
	v_add_f32_e32 v52, v52, v53
	v_add_f32_e32 v54, v54, v52
	s_waitcnt vmcnt(2)
	v_mul_f32_e32 v52, v23, v23
	v_mul_f32_e32 v53, v25, v25
	v_fmac_f32_e32 v52, v22, v22
	v_fmac_f32_e32 v53, v24, v24
	v_add_f32_e32 v52, v52, v53
	v_add_f32_e32 v54, v54, v52
	s_waitcnt vmcnt(1)
	v_mul_f32_e32 v52, v27, v27
	v_mul_f32_e32 v53, v29, v29
	v_fmac_f32_e32 v52, v26, v26
	v_fmac_f32_e32 v53, v28, v28
	v_add_f32_e32 v52, v52, v53
	v_add_f32_e32 v54, v54, v52
	s_waitcnt vmcnt(0)
	v_mul_f32_e32 v52, v31, v31
	v_mul_f32_e32 v53, v33, v33
	v_fmac_f32_e32 v52, v30, v30
	v_fmac_f32_e32 v53, v32, v32
	v_add_f32_e32 v52, v52, v53
	v_add_f32_e32 v45, v54, v52
	ds_bpermute_b32 v46, v0, v45
	s_waitcnt lgkmcnt(0)
	v_add_f32_e32 v45, v45, v46
	ds_bpermute_b32 v46, v40, v45
	s_waitcnt lgkmcnt(0)
	v_add_f32_e32 v45, v45, v46
	ds_bpermute_b32 v46, v41, v45
	s_waitcnt lgkmcnt(0)
	v_add_f32_e32 v45, v45, v46
	ds_bpermute_b32 v46, v42, v45
	s_waitcnt lgkmcnt(0)
	v_add_f32_e32 v45, v45, v46
	ds_bpermute_b32 v46, v43, v45
	s_waitcnt lgkmcnt(0)
	v_add_f32_e32 v45, v45, v46
	ds_bpermute_b32 v46, v44, v45
	s_and_saveexec_b64 s[28:29], s[40:41]
	s_cbranch_execz .LBB0_518
	s_waitcnt lgkmcnt(0)
	v_add_f32_e32 v45, v45, v46
	v_fma_f32 v45, v45, s33, 0.5
	v_cvt_u32_f32_e32 v45, v45
	v_lshl_add_u64 v[46:47], s[70:71], 0, v[34:35]
	global_store_dword v[46:47], v45, off
	s_branch .LBB0_518
